# v23 with all code shifted by 32 bytes (8 s_nop at kernel entry): placement trial
# speedup vs baseline: 1.0056x; 1.0056x over previous
_Z9trunk_fwd6Params:
	s_nop 0
	s_nop 0
	s_nop 0
	s_nop 0
	s_nop 0
	s_nop 0
	s_nop 0
	s_nop 0
	s_load_dwordx4 s[4:7], s[0:1], 0x148
	s_load_dwordx2 s[50:51], s[0:1], 0x160
	v_and_b32_e32 v195, 0x3ff, v0
	v_cmp_gt_u32_e32 vcc, 2, v195
	s_waitcnt lgkmcnt(0)
	v_writelane_b32 v252, s4, 0
	s_nop 1
	v_writelane_b32 v252, s5, 1
	v_writelane_b32 v252, s6, 2
	v_writelane_b32 v252, s7, 3
	s_add_u32 s4, s0, 0x160
	v_writelane_b32 v252, s0, 4
	s_addc_u32 s5, s1, 0
	s_nop 0
	v_writelane_b32 v252, s1, 5
	v_writelane_b32 v252, s4, 6
	s_nop 1
	v_writelane_b32 v252, s5, 7
	s_and_saveexec_b64 s[0:1], vcc
	v_lshl_add_u32 v1, v195, 2, 0
	v_add_u32_e32 v1, 0x22000, v1
	v_mov_b32_e32 v2, 0
	ds_write_b32 v1, v2
	s_or_b64 exec, exec, s[0:1]
	v_readlane_b32 s4, v252, 0
	s_waitcnt lgkmcnt(0)
	s_barrier
	v_readlane_b32 s5, v252, 1
	s_add_u32 s4, s4, 0x64000
	s_getreg_b32 s0, hwreg(HW_REG_XCC_ID, 0, 4)
	v_readlane_b32 s6, v252, 2
	v_readlane_b32 s7, v252, 3
	s_addc_u32 s5, s5, 0
	s_and_b32 s10, s0, 15
	v_cmp_eq_u32_e64 s[6:7], 0, v195
	s_mov_b64 s[0:1], exec
	s_nop 0
	v_writelane_b32 v252, s6, 8
	s_nop 1
	v_writelane_b32 v252, s7, 9
	s_and_b64 s[6:7], s[0:1], s[6:7]
	s_mov_b64 exec, s[6:7]
	s_cbranch_execz .LBB0_5
	s_mov_b64 s[6:7], exec
	v_mbcnt_lo_u32_b32 v1, s6, 0
	v_mbcnt_hi_u32_b32 v1, s7, v1
	v_cmp_eq_u32_e32 vcc, 0, v1
	s_and_b64 s[8:9], exec, vcc
	s_mov_b64 exec, s[8:9]
	s_cbranch_execz .LBB0_5
	s_lshl_b32 s3, s10, 8
	s_bcnt1_i32_b64 s6, s[6:7]
	v_mov_b32_e32 v1, s3
	v_mov_b32_e32 v2, s6
	global_atomic_add v1, v2, s[4:5] offset:1024
